# static priority A/B: s_setprio 1 on the older half (waves 0-3) of the MLA tile loop instead of waves 4-7
# baseline (speedup 1.0000x reference)
; #define GLDS16(g, l) __builtin_amdgcn_global_load_lds((const unsigned*)(g), (unsigned*)(l), 16, 0, 0)
; #define GLDS4(g, l) __builtin_amdgcn_global_load_lds((const unsigned*)(g), (unsigned*)(l), 4, 0, 0)
; DI int tid_pinned() { int t = threadIdx.x; asm volatile("" : "+v"(t)); return t; }
; template <bool DIFF>
; DI void attn_phase(const AttnArgs& a, char* lds) {
;     ...
;     f32x16 o[NM];
; #pragma unroll
;     for (int m = 0; m < NM; ++m)
; #pragma unroll
;       for (int r = 0; r < 16; ++r) o[m][r] = 0.f;
;     const float sbound = a.lamtab_all[DIFF ? 4 : 3];
;     const int usefix_i = __builtin_amdgcn_readfirstlane(sbound < 40.0f ? 1 : 0);
;     const bool usefix = usefix_i != 0;
;     float m_ref = usefix ? 0.f : -1e30f, l_sum = 0.f;
;     f32x16 negm;
; #pragma unroll
;     for (int r = 0; r < 16; ++r) negm[r] = 0.f;
;     if (t_beg < t_end) {
;       const int t2 = tid_pinned();
;       char* pb = lds + (t_beg & 1) * STAGE;
;       const u32 kofs = KOFS(t2) + (u32)t_beg * 64u * (u32)a.ldk, vofs = VOFS(t2) + (u32)t_beg * (u32)(DV * 64);
; #pragma unroll
;       for (int i = 0; i < NKR; ++i) GLDS16(a.K + kofs + i * 64, pb + wave * 1024 + 8192 * i);
; #pragma unroll
;       for (int i = 0; i < NVR; ++i) GLDS16(a.VT + vofs + i * 4096, pb + KBYTES + wave * 1024 + 8192 * i);
;       if (wave == 0) { const int l4 = t_beg * 64 + (t2 & 63); GLDS4(a.pos + l4, pb + KBYTES + VBYTES); GLDS4(a.posf + l4, pb + KBYTES + VBYTES + 256); }
;     }
;     __syncthreads();
; #pragma unroll 1
;     for (int t = t_beg; t < t_end; ++t) {
.LBB0_374:
	s_andn2_b64 vcc, exec, s[74:75]
	s_waitcnt vmcnt(0) lgkmcnt(0)
	s_barrier
	s_cbranch_vccnz .LBB0_369
	v_cvt_f32_i32_e32 v0, v2
	s_lshl_b32 s7, s33, 17
	s_lshl_b32 s5, s5, 21
	s_and_b32 s7, s7, 0x1c00000
	v_cvt_i32_f32_e32 v0, v0
	v_mov_b32_e32 v14, v1
	v_mov_b32_e32 v15, v1
	s_add_i32 s5, s7, s5
	v_ashrrev_i32_e32 v215, 6, v0
	v_mov_b32_e32 v0, v1
	v_mov_b32_e32 v2, v1
	v_mov_b32_e32 v3, v1
	v_mov_b32_e32 v4, v1
	v_mov_b32_e32 v5, v1
	v_mov_b32_e32 v6, v1
	v_mov_b32_e32 v7, v1
	v_mov_b32_e32 v8, v1
	v_mov_b32_e32 v9, v1
	v_mov_b32_e32 v10, v1
	v_mov_b32_e32 v11, v1
	v_mov_b32_e32 v12, v1
	v_mov_b32_e32 v13, v1
	v_mov_b64_e32 v[30:31], v[14:15]
	v_mov_b64_e32 v[46:47], v[14:15]
	v_mov_b64_e32 v[62:63], v[14:15]
	v_mov_b64_e32 v[78:79], v[14:15]
	v_cndmask_b32_e64 v214, 0, 1, s[10:11]
	s_mov_b32 s22, 0
	v_cndmask_b32_e64 v216, v211, 0, s[10:11]
	s_bitset1_b32 s5, 13
	v_mov_b32_e32 v217, 0
	s_mov_b32 s7, 0x20ff4
	s_mov_b32 s52, 64
	v_mov_b64_e32 v[28:29], v[12:13]
	v_mov_b64_e32 v[26:27], v[10:11]
	v_mov_b64_e32 v[24:25], v[8:9]
	v_mov_b64_e32 v[22:23], v[6:7]
	v_mov_b64_e32 v[20:21], v[4:5]
	v_mov_b64_e32 v[18:19], v[2:3]
	v_mov_b64_e32 v[16:17], v[0:1]
	v_mov_b64_e32 v[44:45], v[12:13]
	v_mov_b64_e32 v[42:43], v[10:11]
	v_mov_b64_e32 v[40:41], v[8:9]
	v_mov_b64_e32 v[38:39], v[6:7]
	v_mov_b64_e32 v[36:37], v[4:5]
	v_mov_b64_e32 v[34:35], v[2:3]
	v_mov_b64_e32 v[32:33], v[0:1]
	v_mov_b64_e32 v[60:61], v[12:13]
	v_mov_b64_e32 v[58:59], v[10:11]
	v_mov_b64_e32 v[56:57], v[8:9]
	v_mov_b64_e32 v[54:55], v[6:7]
	v_mov_b64_e32 v[52:53], v[4:5]
	v_mov_b64_e32 v[50:51], v[2:3]
	v_mov_b64_e32 v[48:49], v[0:1]
	v_mov_b64_e32 v[76:77], v[12:13]
	v_mov_b64_e32 v[74:75], v[10:11]
	v_mov_b64_e32 v[72:73], v[8:9]
	v_mov_b64_e32 v[70:71], v[6:7]
	v_mov_b64_e32 v[68:69], v[4:5]
	v_mov_b64_e32 v[66:67], v[2:3]
	v_mov_b64_e32 v[64:65], v[0:1]
	s_cmp_ge_u32 s59, 0x1000
	s_cbranch_scc1 .Lmla_noprio
	s_setprio 1
